# L1 items: skip the redundant re-load of the last sub-chunk's conv inputs
# speedup vs baseline: 1.0785x; 1.0002x over previous
.Lconv_nomask:
	v_lshlrev_b32_e32 v18, 16, v126
	v_and_b32_e32 v19, 0xffff0000, v126
	v_lshlrev_b32_e32 v20, 16, v127
	v_and_b32_e32 v21, 0xffff0000, v127
	v_lshlrev_b32_e32 v22, 16, v128
	v_and_b32_e32 v23, 0xffff0000, v128
	v_lshlrev_b32_e32 v24, 16, v129
	v_and_b32_e32 v25, 0xffff0000, v129
	v_lshlrev_b32_e32 v26, 16, v110
	v_and_b32_e32 v27, 0xffff0000, v110
	v_lshlrev_b32_e32 v28, 16, v111
	v_and_b32_e32 v29, 0xffff0000, v111
	v_lshlrev_b32_e32 v30, 16, v112
	v_and_b32_e32 v31, 0xffff0000, v112
	v_lshlrev_b32_e32 v32, 16, v113
	v_and_b32_e32 v33, 0xffff0000, v113
	s_waitcnt lgkmcnt(4)
	v_pk_fma_f32 v[2:3], v[144:145], v[18:19], v[2:3]
	v_pk_fma_f32 v[4:5], v[146:147], v[20:21], v[4:5]
	v_pk_fma_f32 v[6:7], v[148:149], v[22:23], v[6:7]
	v_pk_fma_f32 v[8:9], v[150:151], v[24:25], v[8:9]
	v_pk_fma_f32 v[14:15], v[152:153], v[26:27], v[14:15]
	v_pk_fma_f32 v[16:17], v[154:155], v[28:29], v[16:17]
	v_pk_fma_f32 v[10:11], v[156:157], v[30:31], v[10:11]
	v_pk_fma_f32 v[12:13], v[158:159], v[32:33], v[12:13]
	ds_read_b128 v[144:147], v188 offset:4096
	ds_read_b128 v[148:151], v188 offset:4112
	ds_read_b128 v[152:155], v196 offset:4096
	ds_read_b128 v[156:159], v196 offset:4112
	v_lshlrev_b32_e32 v18, 16, v122
	v_and_b32_e32 v19, 0xffff0000, v122
	v_lshlrev_b32_e32 v20, 16, v123
	v_and_b32_e32 v21, 0xffff0000, v123
	v_lshlrev_b32_e32 v22, 16, v124
	v_and_b32_e32 v23, 0xffff0000, v124
	v_lshlrev_b32_e32 v24, 16, v125
	v_and_b32_e32 v25, 0xffff0000, v125
	v_lshlrev_b32_e32 v26, 16, v106
	v_and_b32_e32 v27, 0xffff0000, v106
	v_lshlrev_b32_e32 v28, 16, v107
	v_and_b32_e32 v29, 0xffff0000, v107
	v_lshlrev_b32_e32 v30, 16, v108
	v_and_b32_e32 v31, 0xffff0000, v108
	v_lshlrev_b32_e32 v32, 16, v109
	v_and_b32_e32 v33, 0xffff0000, v109
	s_waitcnt lgkmcnt(4)
	v_pk_fma_f32 v[2:3], v[160:161], v[18:19], v[2:3]
	v_pk_fma_f32 v[4:5], v[162:163], v[20:21], v[4:5]
	v_pk_fma_f32 v[6:7], v[164:165], v[22:23], v[6:7]
	v_pk_fma_f32 v[8:9], v[166:167], v[24:25], v[8:9]
	v_pk_fma_f32 v[14:15], v[130:131], v[26:27], v[14:15]
	v_pk_fma_f32 v[16:17], v[132:133], v[28:29], v[16:17]
	v_pk_fma_f32 v[10:11], v[134:135], v[30:31], v[10:11]
	v_pk_fma_f32 v[12:13], v[136:137], v[32:33], v[12:13]
	ds_read_b128 v[160:163], v188 offset:6144
	ds_read_b128 v[164:167], v188 offset:6160
	ds_read_b128 v[130:133], v196 offset:6144
	ds_read_b128 v[134:137], v196 offset:6160
	v_lshlrev_b32_e32 v18, 16, v118
	v_and_b32_e32 v19, 0xffff0000, v118
	v_lshlrev_b32_e32 v20, 16, v119
	v_and_b32_e32 v21, 0xffff0000, v119
	v_lshlrev_b32_e32 v22, 16, v120
	v_and_b32_e32 v23, 0xffff0000, v120
	v_lshlrev_b32_e32 v24, 16, v121
	v_and_b32_e32 v25, 0xffff0000, v121
	v_lshlrev_b32_e32 v26, 16, v102
	v_and_b32_e32 v27, 0xffff0000, v102
	v_lshlrev_b32_e32 v28, 16, v103
	v_and_b32_e32 v29, 0xffff0000, v103
	v_lshlrev_b32_e32 v30, 16, v104
	v_and_b32_e32 v31, 0xffff0000, v104
	v_lshlrev_b32_e32 v32, 16, v105
	v_and_b32_e32 v33, 0xffff0000, v105
	s_waitcnt lgkmcnt(4)
	v_pk_fma_f32 v[2:3], v[144:145], v[18:19], v[2:3]
	v_pk_fma_f32 v[4:5], v[146:147], v[20:21], v[4:5]
	v_pk_fma_f32 v[6:7], v[148:149], v[22:23], v[6:7]
	v_pk_fma_f32 v[8:9], v[150:151], v[24:25], v[8:9]
	v_pk_fma_f32 v[14:15], v[152:153], v[26:27], v[14:15]
	v_pk_fma_f32 v[16:17], v[154:155], v[28:29], v[16:17]
	v_pk_fma_f32 v[10:11], v[156:157], v[30:31], v[10:11]
	v_pk_fma_f32 v[12:13], v[158:159], v[32:33], v[12:13]
	v_lshlrev_b32_e32 v18, 16, v114
	v_and_b32_e32 v19, 0xffff0000, v114
	v_lshlrev_b32_e32 v20, 16, v115
	v_and_b32_e32 v21, 0xffff0000, v115
	v_lshlrev_b32_e32 v22, 16, v116
	v_and_b32_e32 v23, 0xffff0000, v116
	v_lshlrev_b32_e32 v24, 16, v117
	v_and_b32_e32 v25, 0xffff0000, v117
	v_lshlrev_b32_e32 v26, 16, v98
	v_and_b32_e32 v27, 0xffff0000, v98
	v_lshlrev_b32_e32 v28, 16, v99
	v_and_b32_e32 v29, 0xffff0000, v99
	v_lshlrev_b32_e32 v30, 16, v100
	v_and_b32_e32 v31, 0xffff0000, v100
	v_lshlrev_b32_e32 v32, 16, v101
	v_and_b32_e32 v33, 0xffff0000, v101
	s_waitcnt lgkmcnt(0)
	v_pk_fma_f32 v[2:3], v[160:161], v[18:19], v[2:3]
	v_pk_fma_f32 v[4:5], v[162:163], v[20:21], v[4:5]
	v_pk_fma_f32 v[6:7], v[164:165], v[22:23], v[6:7]
	v_pk_fma_f32 v[8:9], v[166:167], v[24:25], v[8:9]
	v_pk_fma_f32 v[14:15], v[130:131], v[26:27], v[14:15]
	v_pk_fma_f32 v[16:17], v[132:133], v[28:29], v[16:17]
	v_pk_fma_f32 v[10:11], v[134:135], v[30:31], v[10:11]
	v_pk_fma_f32 v[12:13], v[136:137], v[32:33], v[12:13]
	v_cvt_pk_bf16_f32 v134, v2, v3
	v_cvt_pk_bf16_f32 v135, v4, v5
	v_cvt_pk_bf16_f32 v136, v6, v7
	ds_write_b128 v212, v[2:5]
	ds_write_b128 v212, v[6:9] offset:16
	ds_write_b128 v212, v[14:17] offset:128
	ds_write_b128 v212, v[10:13] offset:144
	s_waitcnt lgkmcnt(0)
	v_cvt_pk_bf16_f32 v6, v14, v15
	v_cvt_pk_bf16_f32 v7, v16, v17
	ds_read_b128 v[150:153], v213
	ds_read_b128 v[26:29], v213 offset:64
	ds_read_b128 v[14:17], v213 offset:128
	ds_read_b128 v[2:5], v213 offset:192
	s_waitcnt lgkmcnt(0)
	v_cvt_pk_bf16_f32 v137, v8, v9
	v_cvt_pk_bf16_f32 v8, v10, v11
	v_cvt_pk_bf16_f32 v9, v12, v13
	s_add_i32 s37, s37, 16
	s_cmp_eq_u32 s40, 48
	s_cbranch_scc1 .Lconv_nopf
	s_cmp_lg_u32 s40, 48
	s_cselect_b32 s10, s37, 48
	v_or_b32_e32 v20, s10, v184
	v_add_u32_e32 v21, s33, v20
	v_cmp_lt_i32_e32 vcc, 1, v21
	v_cmp_gt_i32_e64 s[10:11], s48, v21
	v_add_u32_e32 v0, -2, v20
	s_and_b64 vcc, vcc, s[10:11]
	v_cndmask_b32_e32 v10, v20, v0, vcc
	v_cmp_lt_i32_e32 vcc, 0, v21
	v_cmp_ge_i32_e64 s[10:11], s3, v21
	s_and_b64 vcc, vcc, s[10:11]
	v_subbrev_co_u32_e32 v12, vcc, 0, v20, vcc
	v_cmp_lt_i32_e32 vcc, -2, v21
	v_cmp_gt_i32_e64 s[10:11], s49, v21
	v_ashrrev_i32_e32 v11, 31, v10
	v_lshlrev_b32_e32 v0, 10, v20
	s_and_b64 vcc, vcc, s[10:11]
	v_lshlrev_b64 v[10:11], 10, v[10:11]
	v_ashrrev_i32_e32 v13, 31, v12
	v_lshl_add_u64 v[18:19], v[140:141], 0, v[0:1]
	v_addc_co_u32_e32 v0, vcc, 0, v20, vcc
	v_lshl_add_u64 v[10:11], v[140:141], 0, v[10:11]
	v_lshlrev_b64 v[12:13], 10, v[12:13]
	v_lshlrev_b32_e32 v0, 10, v0
	v_lshl_add_u64 v[12:13], v[140:141], 0, v[12:13]
	v_lshl_add_u64 v[20:21], v[140:141], 0, v[0:1]
	global_load_dwordx4 v[126:129], v[10:11], off
	global_load_dwordx4 v[110:113], v[10:11], off offset:64
	global_load_dwordx4 v[122:125], v[12:13], off
	global_load_dwordx4 v[106:109], v[12:13], off offset:64
	global_load_dwordx4 v[118:121], v[18:19], off
	global_load_dwordx4 v[102:105], v[18:19], off offset:64
	global_load_dwordx4 v[114:117], v[20:21], off
	global_load_dwordx4 v[98:101], v[20:21], off offset:64
.Lconv_nopf:
	ds_read_b128 v[158:161], v197
	ds_read_b128 v[162:165], v198
	ds_read_b128 v[166:169], v199
	v_mfma_f32_16x16x32_bf16 v[10:13], v[34:37], v[134:137], 0
	s_mov_b64 s[10:11], -1
	v_mfma_f32_16x16x32_bf16 v[18:21], v[42:45], v[134:137], 0
	v_mfma_f32_16x16x32_bf16 v[146:149], v[38:41], v[6:9], v[10:13]
	v_mfma_f32_16x16x32_bf16 v[10:13], v[50:53], v[134:137], 0
	v_mfma_f32_16x16x32_bf16 v[154:157], v[46:49], v[6:9], v[18:21]
	v_mfma_f32_16x16x32_bf16 v[18:21], v[58:61], v[134:137], 0
	v_mfma_f32_16x16x32_bf16 v[130:133], v[54:57], v[6:9], v[10:13]
	v_mfma_f32_16x16x32_bf16 v[10:13], v[66:69], v[134:137], 0
	v_mfma_f32_16x16x32_bf16 v[30:33], v[62:65], v[6:9], v[18:21]
	v_mfma_f32_16x16x32_bf16 v[18:21], v[70:73], v[134:137], 0
	v_mfma_f32_16x16x32_bf16 v[22:25], v[74:77], v[6:9], v[10:13]
	v_mfma_f32_16x16x32_bf16 v[10:13], v[82:85], v[134:137], 0
	v_mfma_f32_16x16x32_bf16 v[134:137], v[86:89], v[134:137], 0
	v_mfma_f32_16x16x32_bf16 v[18:21], v[78:81], v[6:9], v[18:21]
	v_mfma_f32_16x16x32_bf16 v[10:13], v[90:93], v[6:9], v[10:13]
	v_mfma_f32_16x16x32_bf16 v[6:9], v[94:97], v[6:9], v[134:137]
	s_nop 4
	ds_read_b128 v[246:249], v202
	ds_read_b128 v[250:253], v203
	ds_read_b128 v[134:137], v204
	v_mov_b32_e32 v170, 0xbfb8aa3b
	v_mov_b32_e32 v226, 0x3fb17218
	s_waitcnt lgkmcnt(3)
	v_pk_fma_f32 v[146:147], v[146:147], v[170:171], v[158:159] op_sel_hi:[1,0,1]
	v_pk_fma_f32 v[148:149], v[148:149], v[170:171], v[160:161] op_sel_hi:[1,0,1]
	v_pk_fma_f32 v[154:155], v[154:155], v[170:171], v[162:163] op_sel_hi:[1,0,1]
	v_pk_fma_f32 v[156:157], v[156:157], v[170:171], v[164:165] op_sel_hi:[1,0,1]
	v_exp_f32_e32 v146, v146
	v_exp_f32_e32 v147, v147
	v_exp_f32_e32 v148, v148
	v_exp_f32_e32 v149, v149
	v_exp_f32_e32 v154, v154
	v_exp_f32_e32 v155, v155
	v_exp_f32_e32 v156, v156
	v_exp_f32_e32 v157, v157
	v_pk_add_f32 v[146:147], v[146:147], 1.0 op_sel_hi:[1,0]
	v_pk_add_f32 v[148:149], v[148:149], 1.0 op_sel_hi:[1,0]
	v_pk_add_f32 v[154:155], v[154:155], 1.0 op_sel_hi:[1,0]
	v_pk_add_f32 v[156:157], v[156:157], 1.0 op_sel_hi:[1,0]
	v_rcp_f32_e32 v146, v146
	v_rcp_f32_e32 v147, v147
	v_rcp_f32_e32 v148, v148
	v_rcp_f32_e32 v149, v149
	v_rcp_f32_e32 v154, v154
	v_rcp_f32_e32 v155, v155
	v_rcp_f32_e32 v156, v156
	v_rcp_f32_e32 v157, v157
	v_pk_mul_f32 v[166:167], v[166:167], v[146:147]
	v_pk_mul_f32 v[168:169], v[168:169], v[148:149]
	v_exp_f32_e32 v146, v166
	v_exp_f32_e32 v147, v167
	v_exp_f32_e32 v148, v168
	v_exp_f32_e32 v149, v169
	v_pk_mul_f32 v[158:159], v[166:167], v[226:227] op_sel_hi:[1,0]
	v_pk_mul_f32 v[160:161], v[168:169], v[226:227] op_sel_hi:[1,0]
	v_pk_fma_f32 v[162:163], v[158:159], 0.5, 1.0 op_sel_hi:[1,0,0]
	v_pk_fma_f32 v[164:165], v[160:161], 0.5, 1.0 op_sel_hi:[1,0,0]
	v_pk_mul_f32 v[162:163], v[162:163], v[158:159] neg_lo:[0,1] neg_hi:[0,1]
	v_pk_mul_f32 v[164:165], v[164:165], v[160:161] neg_lo:[0,1] neg_hi:[0,1]
	v_cmp_lt_f32_e32 vcc, s72, v158
	v_cmp_lt_f32_e64 s[12:13], s72, v159
	v_cmp_lt_f32_e64 s[14:15], s72, v160
	v_cmp_lt_f32_e64 s[16:17], s72, v161
	v_pk_fma_f32 v[158:159], v[146:147], v[146:147], 1.0 op_sel_hi:[1,1,0] neg_lo:[1,0,0] neg_hi:[1,0,0]
	v_pk_fma_f32 v[160:161], v[148:149], v[148:149], 1.0 op_sel_hi:[1,1,0] neg_lo:[1,0,0] neg_hi:[1,0,0]
	v_cndmask_b32_e32 v158, v158, v162, vcc
	v_cndmask_b32_e64 v159, v159, v163, s[12:13]
	v_cndmask_b32_e64 v160, v160, v164, s[14:15]
	v_cndmask_b32_e64 v161, v161, v165, s[16:17]
	v_sqrt_f32_e32 v158, v158
	v_sqrt_f32_e32 v159, v159
	v_sqrt_f32_e32 v160, v160
	v_sqrt_f32_e32 v161, v161
	v_pk_mul_f32 v[154:155], v[154:155], v[158:159]
	v_pk_mul_f32 v[156:157], v[156:157], v[160:161]
	v_pk_mul_f32 v[150:151], v[150:151], v[154:155]
	v_pk_mul_f32 v[152:153], v[152:153], v[156:157]
	v_cvt_pkrtz_f16_f32 v162, v166, v150
	v_cvt_pkrtz_f16_f32 v163, v167, v151
	v_cvt_pkrtz_f16_f32 v164, v168, v152
	v_cvt_pkrtz_f16_f32 v165, v169, v153
	global_store_dwordx4 v[142:143], v[162:165], off offset:-2048
	ds_read_b128 v[158:161], v205
	ds_read_b128 v[162:165], v206
	ds_read_b128 v[166:169], v207
	s_waitcnt lgkmcnt(3)
	v_pk_fma_f32 v[130:131], v[130:131], v[170:171], v[246:247] op_sel_hi:[1,0,1]
	v_pk_fma_f32 v[132:133], v[132:133], v[170:171], v[248:249] op_sel_hi:[1,0,1]
	v_pk_fma_f32 v[30:31], v[30:31], v[170:171], v[250:251] op_sel_hi:[1,0,1]
	v_pk_fma_f32 v[32:33], v[32:33], v[170:171], v[252:253] op_sel_hi:[1,0,1]
	v_exp_f32_e32 v130, v130
	v_exp_f32_e32 v131, v131
	v_exp_f32_e32 v132, v132
	v_exp_f32_e32 v133, v133
	v_exp_f32_e32 v30, v30
	v_exp_f32_e32 v31, v31
	v_exp_f32_e32 v32, v32
	v_exp_f32_e32 v33, v33
	v_pk_add_f32 v[130:131], v[130:131], 1.0 op_sel_hi:[1,0]
	v_pk_add_f32 v[132:133], v[132:133], 1.0 op_sel_hi:[1,0]
	v_pk_add_f32 v[30:31], v[30:31], 1.0 op_sel_hi:[1,0]
	v_pk_add_f32 v[32:33], v[32:33], 1.0 op_sel_hi:[1,0]
	v_rcp_f32_e32 v130, v130
	v_rcp_f32_e32 v131, v131
	v_rcp_f32_e32 v132, v132
	v_rcp_f32_e32 v133, v133
	v_rcp_f32_e32 v30, v30
	v_rcp_f32_e32 v31, v31
	v_rcp_f32_e32 v32, v32
	v_rcp_f32_e32 v33, v33
	v_pk_mul_f32 v[134:135], v[134:135], v[130:131]
	v_pk_mul_f32 v[136:137], v[136:137], v[132:133]
	v_exp_f32_e32 v130, v134
	v_exp_f32_e32 v131, v135
	v_exp_f32_e32 v132, v136
	v_exp_f32_e32 v133, v137
	v_pk_mul_f32 v[246:247], v[134:135], v[226:227] op_sel_hi:[1,0]
	v_pk_mul_f32 v[248:249], v[136:137], v[226:227] op_sel_hi:[1,0]
	v_pk_fma_f32 v[250:251], v[246:247], 0.5, 1.0 op_sel_hi:[1,0,0]
	v_pk_fma_f32 v[252:253], v[248:249], 0.5, 1.0 op_sel_hi:[1,0,0]
	v_pk_mul_f32 v[250:251], v[250:251], v[246:247] neg_lo:[0,1] neg_hi:[0,1]
	v_pk_mul_f32 v[252:253], v[252:253], v[248:249] neg_lo:[0,1] neg_hi:[0,1]
	v_cmp_lt_f32_e32 vcc, s72, v246
	v_cmp_lt_f32_e64 s[12:13], s72, v247
	v_cmp_lt_f32_e64 s[14:15], s72, v248
	v_cmp_lt_f32_e64 s[16:17], s72, v249
	v_pk_fma_f32 v[246:247], v[130:131], v[130:131], 1.0 op_sel_hi:[1,1,0] neg_lo:[1,0,0] neg_hi:[1,0,0]
	v_pk_fma_f32 v[248:249], v[132:133], v[132:133], 1.0 op_sel_hi:[1,1,0] neg_lo:[1,0,0] neg_hi:[1,0,0]
	v_cndmask_b32_e32 v246, v246, v250, vcc
	v_cndmask_b32_e64 v247, v247, v251, s[12:13]
	v_cndmask_b32_e64 v248, v248, v252, s[14:15]
	v_cndmask_b32_e64 v249, v249, v253, s[16:17]
	v_sqrt_f32_e32 v246, v246
	v_sqrt_f32_e32 v247, v247
	v_sqrt_f32_e32 v248, v248
	v_sqrt_f32_e32 v249, v249
	v_pk_mul_f32 v[30:31], v[30:31], v[246:247]
	v_pk_mul_f32 v[32:33], v[32:33], v[248:249]
	v_pk_mul_f32 v[26:27], v[26:27], v[30:31]
	v_pk_mul_f32 v[28:29], v[28:29], v[32:33]
	v_cvt_pkrtz_f16_f32 v250, v134, v26
	v_cvt_pkrtz_f16_f32 v251, v135, v27
	v_cvt_pkrtz_f16_f32 v252, v136, v28
	v_cvt_pkrtz_f16_f32 v253, v137, v29
	global_store_dwordx4 v[142:143], v[250:253], off offset:-1024
	ds_read_b128 v[246:249], v208
	ds_read_b128 v[250:253], v209
	ds_read_b128 v[134:137], v210
	s_waitcnt lgkmcnt(3)
	v_pk_fma_f32 v[22:23], v[22:23], v[170:171], v[158:159] op_sel_hi:[1,0,1]
	v_pk_fma_f32 v[24:25], v[24:25], v[170:171], v[160:161] op_sel_hi:[1,0,1]
	v_pk_fma_f32 v[18:19], v[18:19], v[170:171], v[162:163] op_sel_hi:[1,0,1]
	v_pk_fma_f32 v[20:21], v[20:21], v[170:171], v[164:165] op_sel_hi:[1,0,1]
	v_exp_f32_e32 v22, v22
	v_exp_f32_e32 v23, v23
	v_exp_f32_e32 v24, v24
	v_exp_f32_e32 v25, v25
	v_exp_f32_e32 v18, v18
	v_exp_f32_e32 v19, v19
	v_exp_f32_e32 v20, v20
	v_exp_f32_e32 v21, v21
	v_pk_add_f32 v[22:23], v[22:23], 1.0 op_sel_hi:[1,0]
	v_pk_add_f32 v[24:25], v[24:25], 1.0 op_sel_hi:[1,0]
	v_pk_add_f32 v[18:19], v[18:19], 1.0 op_sel_hi:[1,0]
	v_pk_add_f32 v[20:21], v[20:21], 1.0 op_sel_hi:[1,0]
	v_rcp_f32_e32 v22, v22
	v_rcp_f32_e32 v23, v23
	v_rcp_f32_e32 v24, v24
	v_rcp_f32_e32 v25, v25
	v_rcp_f32_e32 v18, v18
	v_rcp_f32_e32 v19, v19
	v_rcp_f32_e32 v20, v20
	v_rcp_f32_e32 v21, v21
	v_pk_mul_f32 v[166:167], v[166:167], v[22:23]
	v_pk_mul_f32 v[168:169], v[168:169], v[24:25]
	v_exp_f32_e32 v22, v166
	v_exp_f32_e32 v23, v167
	v_exp_f32_e32 v24, v168
	v_exp_f32_e32 v25, v169
	v_pk_mul_f32 v[158:159], v[166:167], v[226:227] op_sel_hi:[1,0]
	v_pk_mul_f32 v[160:161], v[168:169], v[226:227] op_sel_hi:[1,0]
	v_pk_fma_f32 v[162:163], v[158:159], 0.5, 1.0 op_sel_hi:[1,0,0]
	v_pk_fma_f32 v[164:165], v[160:161], 0.5, 1.0 op_sel_hi:[1,0,0]
	v_pk_mul_f32 v[162:163], v[162:163], v[158:159] neg_lo:[0,1] neg_hi:[0,1]
	v_pk_mul_f32 v[164:165], v[164:165], v[160:161] neg_lo:[0,1] neg_hi:[0,1]
	v_cmp_lt_f32_e32 vcc, s72, v158
	v_cmp_lt_f32_e64 s[12:13], s72, v159
	v_cmp_lt_f32_e64 s[14:15], s72, v160
	v_cmp_lt_f32_e64 s[16:17], s72, v161
	v_pk_fma_f32 v[158:159], v[22:23], v[22:23], 1.0 op_sel_hi:[1,1,0] neg_lo:[1,0,0] neg_hi:[1,0,0]
	v_pk_fma_f32 v[160:161], v[24:25], v[24:25], 1.0 op_sel_hi:[1,1,0] neg_lo:[1,0,0] neg_hi:[1,0,0]
	v_cndmask_b32_e32 v158, v158, v162, vcc
	v_cndmask_b32_e64 v159, v159, v163, s[12:13]
	v_cndmask_b32_e64 v160, v160, v164, s[14:15]
	v_cndmask_b32_e64 v161, v161, v165, s[16:17]
	v_sqrt_f32_e32 v158, v158
	v_sqrt_f32_e32 v159, v159
	v_sqrt_f32_e32 v160, v160
	v_sqrt_f32_e32 v161, v161
	v_pk_mul_f32 v[18:19], v[18:19], v[158:159]
	v_pk_mul_f32 v[20:21], v[20:21], v[160:161]
	v_pk_mul_f32 v[14:15], v[14:15], v[18:19]
	v_pk_mul_f32 v[16:17], v[16:17], v[20:21]
	v_cvt_pkrtz_f16_f32 v162, v166, v14
	v_cvt_pkrtz_f16_f32 v163, v167, v15
	v_cvt_pkrtz_f16_f32 v164, v168, v16
	v_cvt_pkrtz_f16_f32 v165, v169, v17
	global_store_dwordx4 v[142:143], v[162:165], off
	s_waitcnt lgkmcnt(0)
	v_pk_fma_f32 v[10:11], v[10:11], v[170:171], v[246:247] op_sel_hi:[1,0,1]
	v_pk_fma_f32 v[12:13], v[12:13], v[170:171], v[248:249] op_sel_hi:[1,0,1]
	v_pk_fma_f32 v[6:7], v[6:7], v[170:171], v[250:251] op_sel_hi:[1,0,1]
	v_pk_fma_f32 v[8:9], v[8:9], v[170:171], v[252:253] op_sel_hi:[1,0,1]
	v_exp_f32_e32 v10, v10
	v_exp_f32_e32 v11, v11
	v_exp_f32_e32 v12, v12
	v_exp_f32_e32 v13, v13
	v_exp_f32_e32 v6, v6
	v_exp_f32_e32 v7, v7
	v_exp_f32_e32 v8, v8
	v_exp_f32_e32 v9, v9
	v_pk_add_f32 v[10:11], v[10:11], 1.0 op_sel_hi:[1,0]
	v_pk_add_f32 v[12:13], v[12:13], 1.0 op_sel_hi:[1,0]
	v_pk_add_f32 v[6:7], v[6:7], 1.0 op_sel_hi:[1,0]
	v_pk_add_f32 v[8:9], v[8:9], 1.0 op_sel_hi:[1,0]
	v_rcp_f32_e32 v10, v10
	v_rcp_f32_e32 v11, v11
	v_rcp_f32_e32 v12, v12
	v_rcp_f32_e32 v13, v13
	v_rcp_f32_e32 v6, v6
	v_rcp_f32_e32 v7, v7
	v_rcp_f32_e32 v8, v8
	v_rcp_f32_e32 v9, v9
	v_pk_mul_f32 v[134:135], v[134:135], v[10:11]
	v_pk_mul_f32 v[136:137], v[136:137], v[12:13]
	v_exp_f32_e32 v10, v134
	v_exp_f32_e32 v11, v135
	v_exp_f32_e32 v12, v136
	v_exp_f32_e32 v13, v137
	v_pk_mul_f32 v[246:247], v[134:135], v[226:227] op_sel_hi:[1,0]
	v_pk_mul_f32 v[248:249], v[136:137], v[226:227] op_sel_hi:[1,0]
	v_pk_fma_f32 v[250:251], v[246:247], 0.5, 1.0 op_sel_hi:[1,0,0]
	v_pk_fma_f32 v[252:253], v[248:249], 0.5, 1.0 op_sel_hi:[1,0,0]
	v_pk_mul_f32 v[250:251], v[250:251], v[246:247] neg_lo:[0,1] neg_hi:[0,1]
	v_pk_mul_f32 v[252:253], v[252:253], v[248:249] neg_lo:[0,1] neg_hi:[0,1]
	v_cmp_lt_f32_e32 vcc, s72, v246
	v_cmp_lt_f32_e64 s[12:13], s72, v247
	v_cmp_lt_f32_e64 s[14:15], s72, v248
	v_cmp_lt_f32_e64 s[16:17], s72, v249
	v_pk_fma_f32 v[246:247], v[10:11], v[10:11], 1.0 op_sel_hi:[1,1,0] neg_lo:[1,0,0] neg_hi:[1,0,0]
	v_pk_fma_f32 v[248:249], v[12:13], v[12:13], 1.0 op_sel_hi:[1,1,0] neg_lo:[1,0,0] neg_hi:[1,0,0]
	v_cndmask_b32_e32 v246, v246, v250, vcc
	v_cndmask_b32_e64 v247, v247, v251, s[12:13]
	v_cndmask_b32_e64 v248, v248, v252, s[14:15]
	v_cndmask_b32_e64 v249, v249, v253, s[16:17]
	v_sqrt_f32_e32 v246, v246
	v_sqrt_f32_e32 v247, v247
	v_sqrt_f32_e32 v248, v248
	v_sqrt_f32_e32 v249, v249
	v_pk_mul_f32 v[6:7], v[6:7], v[246:247]
	v_pk_mul_f32 v[8:9], v[8:9], v[248:249]
	v_pk_mul_f32 v[2:3], v[2:3], v[6:7]
	v_pk_mul_f32 v[4:5], v[4:5], v[8:9]
	v_cvt_pkrtz_f16_f32 v250, v134, v2
	v_cvt_pkrtz_f16_f32 v251, v135, v3
	v_cvt_pkrtz_f16_f32 v252, v136, v4
	v_cvt_pkrtz_f16_f32 v253, v137, v5
	global_store_dwordx4 v[142:143], v[250:253], off offset:1024
	s_and_b64 vcc, exec, s[44:45]
	s_cbranch_vccz .LBB0_341
	s_mov_b32 s10, 0x10001
	s_mov_b32 s11, 0x10001
	s_mov_b64 s[12:13], exec
	s_mov_b64 exec, s[10:11]
	v_fma_f32 v150, v172, v150, v214
	v_mul_f32_e32 v146, v146, v172
	v_fma_f32 v151, v173, v151, v215
	v_mul_f32_e32 v147, v147, v173
	v_fma_f32 v152, v174, v152, v216
	v_mul_f32_e32 v148, v148, v174
	v_fma_f32 v153, v175, v153, v217
	v_mul_f32_e32 v149, v149, v175
	v_fma_f32 v26, v176, v26, v218
	v_mul_f32_e32 v130, v130, v176
	v_fma_f32 v27, v177, v27, v219
	v_mul_f32_e32 v131, v131, v177
	v_fma_f32 v28, v178, v28, v220
	v_mul_f32_e32 v132, v132, v178
	v_fma_f32 v29, v179, v29, v221
	v_mul_f32_e32 v133, v133, v179
	v_fma_f32 v14, v180, v14, v222
	v_mul_f32_e32 v22, v22, v180
	v_fma_f32 v15, v181, v15, v223
	v_mul_f32_e32 v23, v23, v181
	v_fma_f32 v16, v182, v16, v224
	v_mul_f32_e32 v24, v24, v182
	v_fma_f32 v17, v183, v17, v225
	v_mul_f32_e32 v25, v25, v183
	v_fma_f32 v2, v192, v2, v234
	v_mul_f32_e32 v10, v10, v192
	v_fma_f32 v3, v193, v3, v235
	v_mul_f32_e32 v11, v11, v193
	v_fma_f32 v4, v194, v4, v236
	v_mul_f32_e32 v12, v12, v194
	v_fma_f32 v5, v195, v5, v237
	v_mul_f32_e32 v13, v13, v195
	s_mov_b64 exec, s[12:13]
	s_nop 4
	v_fmac_f32_dpp v150, v150, v146 row_shl:1 row_mask:0xf bank_mask:0xf bound_ctrl:1
	v_mul_f32_dpp v146, v146, v146 row_shl:1 row_mask:0xf bank_mask:0xf
	v_fmac_f32_dpp v151, v151, v147 row_shl:1 row_mask:0xf bank_mask:0xf bound_ctrl:1
	v_mul_f32_dpp v147, v147, v147 row_shl:1 row_mask:0xf bank_mask:0xf
	v_fmac_f32_dpp v152, v152, v148 row_shl:1 row_mask:0xf bank_mask:0xf bound_ctrl:1
	v_mul_f32_dpp v148, v148, v148 row_shl:1 row_mask:0xf bank_mask:0xf
	v_fmac_f32_dpp v153, v153, v149 row_shl:1 row_mask:0xf bank_mask:0xf bound_ctrl:1
	v_mul_f32_dpp v149, v149, v149 row_shl:1 row_mask:0xf bank_mask:0xf
	v_fmac_f32_dpp v26, v26, v130 row_shl:1 row_mask:0xf bank_mask:0xf bound_ctrl:1
	v_mul_f32_dpp v130, v130, v130 row_shl:1 row_mask:0xf bank_mask:0xf
	v_fmac_f32_dpp v27, v27, v131 row_shl:1 row_mask:0xf bank_mask:0xf bound_ctrl:1
	v_mul_f32_dpp v131, v131, v131 row_shl:1 row_mask:0xf bank_mask:0xf
	v_fmac_f32_dpp v28, v28, v132 row_shl:1 row_mask:0xf bank_mask:0xf bound_ctrl:1
	v_mul_f32_dpp v132, v132, v132 row_shl:1 row_mask:0xf bank_mask:0xf
	v_fmac_f32_dpp v29, v29, v133 row_shl:1 row_mask:0xf bank_mask:0xf bound_ctrl:1
	v_mul_f32_dpp v133, v133, v133 row_shl:1 row_mask:0xf bank_mask:0xf
	v_fmac_f32_dpp v14, v14, v22 row_shl:1 row_mask:0xf bank_mask:0xf bound_ctrl:1
	v_mul_f32_dpp v22, v22, v22 row_shl:1 row_mask:0xf bank_mask:0xf
	v_fmac_f32_dpp v15, v15, v23 row_shl:1 row_mask:0xf bank_mask:0xf bound_ctrl:1
	v_mul_f32_dpp v23, v23, v23 row_shl:1 row_mask:0xf bank_mask:0xf
	v_fmac_f32_dpp v16, v16, v24 row_shl:1 row_mask:0xf bank_mask:0xf bound_ctrl:1
	v_mul_f32_dpp v24, v24, v24 row_shl:1 row_mask:0xf bank_mask:0xf
	v_fmac_f32_dpp v17, v17, v25 row_shl:1 row_mask:0xf bank_mask:0xf bound_ctrl:1
	v_mul_f32_dpp v25, v25, v25 row_shl:1 row_mask:0xf bank_mask:0xf
	v_fmac_f32_dpp v2, v2, v10 row_shl:1 row_mask:0xf bank_mask:0xf bound_ctrl:1
	v_mul_f32_dpp v10, v10, v10 row_shl:1 row_mask:0xf bank_mask:0xf
	v_fmac_f32_dpp v3, v3, v11 row_shl:1 row_mask:0xf bank_mask:0xf bound_ctrl:1
	v_mul_f32_dpp v11, v11, v11 row_shl:1 row_mask:0xf bank_mask:0xf
	v_fmac_f32_dpp v4, v4, v12 row_shl:1 row_mask:0xf bank_mask:0xf bound_ctrl:1
	v_mul_f32_dpp v12, v12, v12 row_shl:1 row_mask:0xf bank_mask:0xf
	v_fmac_f32_dpp v5, v5, v13 row_shl:1 row_mask:0xf bank_mask:0xf bound_ctrl:1
	v_mul_f32_dpp v13, v13, v13 row_shl:1 row_mask:0xf bank_mask:0xf
	v_fmac_f32_dpp v150, v150, v146 row_shl:2 row_mask:0xf bank_mask:0xf bound_ctrl:1
	v_mul_f32_dpp v146, v146, v146 row_shl:2 row_mask:0xf bank_mask:0xf
	v_fmac_f32_dpp v151, v151, v147 row_shl:2 row_mask:0xf bank_mask:0xf bound_ctrl:1
	v_mul_f32_dpp v147, v147, v147 row_shl:2 row_mask:0xf bank_mask:0xf
	v_fmac_f32_dpp v152, v152, v148 row_shl:2 row_mask:0xf bank_mask:0xf bound_ctrl:1
	v_mul_f32_dpp v148, v148, v148 row_shl:2 row_mask:0xf bank_mask:0xf
	v_fmac_f32_dpp v153, v153, v149 row_shl:2 row_mask:0xf bank_mask:0xf bound_ctrl:1
	v_mul_f32_dpp v149, v149, v149 row_shl:2 row_mask:0xf bank_mask:0xf
	v_fmac_f32_dpp v26, v26, v130 row_shl:2 row_mask:0xf bank_mask:0xf bound_ctrl:1
	v_mul_f32_dpp v130, v130, v130 row_shl:2 row_mask:0xf bank_mask:0xf
	v_fmac_f32_dpp v27, v27, v131 row_shl:2 row_mask:0xf bank_mask:0xf bound_ctrl:1
	v_mul_f32_dpp v131, v131, v131 row_shl:2 row_mask:0xf bank_mask:0xf
	v_fmac_f32_dpp v28, v28, v132 row_shl:2 row_mask:0xf bank_mask:0xf bound_ctrl:1
	v_mul_f32_dpp v132, v132, v132 row_shl:2 row_mask:0xf bank_mask:0xf
	v_fmac_f32_dpp v29, v29, v133 row_shl:2 row_mask:0xf bank_mask:0xf bound_ctrl:1
	v_mul_f32_dpp v133, v133, v133 row_shl:2 row_mask:0xf bank_mask:0xf
	v_fmac_f32_dpp v14, v14, v22 row_shl:2 row_mask:0xf bank_mask:0xf bound_ctrl:1
	v_mul_f32_dpp v22, v22, v22 row_shl:2 row_mask:0xf bank_mask:0xf
	v_fmac_f32_dpp v15, v15, v23 row_shl:2 row_mask:0xf bank_mask:0xf bound_ctrl:1
	v_mul_f32_dpp v23, v23, v23 row_shl:2 row_mask:0xf bank_mask:0xf
	v_fmac_f32_dpp v16, v16, v24 row_shl:2 row_mask:0xf bank_mask:0xf bound_ctrl:1
	v_mul_f32_dpp v24, v24, v24 row_shl:2 row_mask:0xf bank_mask:0xf
	v_fmac_f32_dpp v17, v17, v25 row_shl:2 row_mask:0xf bank_mask:0xf bound_ctrl:1
	v_mul_f32_dpp v25, v25, v25 row_shl:2 row_mask:0xf bank_mask:0xf
	v_fmac_f32_dpp v2, v2, v10 row_shl:2 row_mask:0xf bank_mask:0xf bound_ctrl:1
	v_mul_f32_dpp v10, v10, v10 row_shl:2 row_mask:0xf bank_mask:0xf
	v_fmac_f32_dpp v3, v3, v11 row_shl:2 row_mask:0xf bank_mask:0xf bound_ctrl:1
	v_mul_f32_dpp v11, v11, v11 row_shl:2 row_mask:0xf bank_mask:0xf
	v_fmac_f32_dpp v4, v4, v12 row_shl:2 row_mask:0xf bank_mask:0xf bound_ctrl:1
	v_mul_f32_dpp v12, v12, v12 row_shl:2 row_mask:0xf bank_mask:0xf
	v_fmac_f32_dpp v5, v5, v13 row_shl:2 row_mask:0xf bank_mask:0xf bound_ctrl:1
	v_mul_f32_dpp v13, v13, v13 row_shl:2 row_mask:0xf bank_mask:0xf
	v_fmac_f32_dpp v150, v150, v146 row_shl:4 row_mask:0xf bank_mask:0xf bound_ctrl:1
	v_mul_f32_dpp v146, v146, v146 row_shl:4 row_mask:0xf bank_mask:0xf
	v_fmac_f32_dpp v151, v151, v147 row_shl:4 row_mask:0xf bank_mask:0xf bound_ctrl:1
	v_mul_f32_dpp v147, v147, v147 row_shl:4 row_mask:0xf bank_mask:0xf
	v_fmac_f32_dpp v152, v152, v148 row_shl:4 row_mask:0xf bank_mask:0xf bound_ctrl:1
	v_mul_f32_dpp v148, v148, v148 row_shl:4 row_mask:0xf bank_mask:0xf
	v_fmac_f32_dpp v153, v153, v149 row_shl:4 row_mask:0xf bank_mask:0xf bound_ctrl:1
	v_mul_f32_dpp v149, v149, v149 row_shl:4 row_mask:0xf bank_mask:0xf
	v_fmac_f32_dpp v26, v26, v130 row_shl:4 row_mask:0xf bank_mask:0xf bound_ctrl:1
	v_mul_f32_dpp v130, v130, v130 row_shl:4 row_mask:0xf bank_mask:0xf
	v_fmac_f32_dpp v27, v27, v131 row_shl:4 row_mask:0xf bank_mask:0xf bound_ctrl:1
	v_mul_f32_dpp v131, v131, v131 row_shl:4 row_mask:0xf bank_mask:0xf
	v_fmac_f32_dpp v28, v28, v132 row_shl:4 row_mask:0xf bank_mask:0xf bound_ctrl:1
	v_mul_f32_dpp v132, v132, v132 row_shl:4 row_mask:0xf bank_mask:0xf
	v_fmac_f32_dpp v29, v29, v133 row_shl:4 row_mask:0xf bank_mask:0xf bound_ctrl:1
	v_mul_f32_dpp v133, v133, v133 row_shl:4 row_mask:0xf bank_mask:0xf
	v_fmac_f32_dpp v14, v14, v22 row_shl:4 row_mask:0xf bank_mask:0xf bound_ctrl:1
	v_mul_f32_dpp v22, v22, v22 row_shl:4 row_mask:0xf bank_mask:0xf
	v_fmac_f32_dpp v15, v15, v23 row_shl:4 row_mask:0xf bank_mask:0xf bound_ctrl:1
	v_mul_f32_dpp v23, v23, v23 row_shl:4 row_mask:0xf bank_mask:0xf
	v_fmac_f32_dpp v16, v16, v24 row_shl:4 row_mask:0xf bank_mask:0xf bound_ctrl:1
	v_mul_f32_dpp v24, v24, v24 row_shl:4 row_mask:0xf bank_mask:0xf
	v_fmac_f32_dpp v17, v17, v25 row_shl:4 row_mask:0xf bank_mask:0xf bound_ctrl:1
	v_mul_f32_dpp v25, v25, v25 row_shl:4 row_mask:0xf bank_mask:0xf
	v_fmac_f32_dpp v2, v2, v10 row_shl:4 row_mask:0xf bank_mask:0xf bound_ctrl:1
	v_mul_f32_dpp v10, v10, v10 row_shl:4 row_mask:0xf bank_mask:0xf
	v_fmac_f32_dpp v3, v3, v11 row_shl:4 row_mask:0xf bank_mask:0xf bound_ctrl:1
	v_mul_f32_dpp v11, v11, v11 row_shl:4 row_mask:0xf bank_mask:0xf
	v_fmac_f32_dpp v4, v4, v12 row_shl:4 row_mask:0xf bank_mask:0xf bound_ctrl:1
	v_mul_f32_dpp v12, v12, v12 row_shl:4 row_mask:0xf bank_mask:0xf
	v_fmac_f32_dpp v5, v5, v13 row_shl:4 row_mask:0xf bank_mask:0xf bound_ctrl:1
	v_mul_f32_dpp v13, v13, v13 row_shl:4 row_mask:0xf bank_mask:0xf
	v_fmac_f32_dpp v150, v150, v146 row_shl:8 row_mask:0xf bank_mask:0xf bound_ctrl:1
	v_mul_f32_dpp v146, v146, v146 row_shl:8 row_mask:0xf bank_mask:0xf
	v_fmac_f32_dpp v151, v151, v147 row_shl:8 row_mask:0xf bank_mask:0xf bound_ctrl:1
	v_mul_f32_dpp v147, v147, v147 row_shl:8 row_mask:0xf bank_mask:0xf
	v_fmac_f32_dpp v152, v152, v148 row_shl:8 row_mask:0xf bank_mask:0xf bound_ctrl:1
	v_mul_f32_dpp v148, v148, v148 row_shl:8 row_mask:0xf bank_mask:0xf
	v_fmac_f32_dpp v153, v153, v149 row_shl:8 row_mask:0xf bank_mask:0xf bound_ctrl:1
	v_mul_f32_dpp v149, v149, v149 row_shl:8 row_mask:0xf bank_mask:0xf
	v_fmac_f32_dpp v26, v26, v130 row_shl:8 row_mask:0xf bank_mask:0xf bound_ctrl:1
	v_mul_f32_dpp v130, v130, v130 row_shl:8 row_mask:0xf bank_mask:0xf
	v_fmac_f32_dpp v27, v27, v131 row_shl:8 row_mask:0xf bank_mask:0xf bound_ctrl:1
	v_mul_f32_dpp v131, v131, v131 row_shl:8 row_mask:0xf bank_mask:0xf
	v_fmac_f32_dpp v28, v28, v132 row_shl:8 row_mask:0xf bank_mask:0xf bound_ctrl:1
	v_mul_f32_dpp v132, v132, v132 row_shl:8 row_mask:0xf bank_mask:0xf
	v_fmac_f32_dpp v29, v29, v133 row_shl:8 row_mask:0xf bank_mask:0xf bound_ctrl:1
	v_mul_f32_dpp v133, v133, v133 row_shl:8 row_mask:0xf bank_mask:0xf
	v_fmac_f32_dpp v14, v14, v22 row_shl:8 row_mask:0xf bank_mask:0xf bound_ctrl:1
	v_mul_f32_dpp v22, v22, v22 row_shl:8 row_mask:0xf bank_mask:0xf
	v_fmac_f32_dpp v15, v15, v23 row_shl:8 row_mask:0xf bank_mask:0xf bound_ctrl:1
	v_mul_f32_dpp v23, v23, v23 row_shl:8 row_mask:0xf bank_mask:0xf
	v_fmac_f32_dpp v16, v16, v24 row_shl:8 row_mask:0xf bank_mask:0xf bound_ctrl:1
	v_mul_f32_dpp v24, v24, v24 row_shl:8 row_mask:0xf bank_mask:0xf
	v_fmac_f32_dpp v17, v17, v25 row_shl:8 row_mask:0xf bank_mask:0xf bound_ctrl:1
	v_mul_f32_dpp v25, v25, v25 row_shl:8 row_mask:0xf bank_mask:0xf
	v_fmac_f32_dpp v2, v2, v10 row_shl:8 row_mask:0xf bank_mask:0xf bound_ctrl:1
	v_mul_f32_dpp v10, v10, v10 row_shl:8 row_mask:0xf bank_mask:0xf
	v_fmac_f32_dpp v3, v3, v11 row_shl:8 row_mask:0xf bank_mask:0xf bound_ctrl:1
	v_mul_f32_dpp v11, v11, v11 row_shl:8 row_mask:0xf bank_mask:0xf
	v_fmac_f32_dpp v4, v4, v12 row_shl:8 row_mask:0xf bank_mask:0xf bound_ctrl:1
	v_mul_f32_dpp v12, v12, v12 row_shl:8 row_mask:0xf bank_mask:0xf
	v_fmac_f32_dpp v5, v5, v13 row_shl:8 row_mask:0xf bank_mask:0xf bound_ctrl:1
	v_mul_f32_dpp v13, v13, v13 row_shl:8 row_mask:0xf bank_mask:0xf
	v_mov_b64_e32 v[172:173], v[146:147]
	v_mov_b64_e32 v[214:215], v[150:151]
	v_mov_b64_e32 v[174:175], v[148:149]
	v_mov_b64_e32 v[216:217], v[152:153]
	v_mov_b64_e32 v[176:177], v[130:131]
	v_mov_b64_e32 v[218:219], v[26:27]
	v_mov_b64_e32 v[178:179], v[132:133]
	v_mov_b64_e32 v[220:221], v[28:29]
	v_mov_b64_e32 v[180:181], v[22:23]
	v_mov_b64_e32 v[222:223], v[14:15]
	v_mov_b64_e32 v[182:183], v[24:25]
	v_mov_b64_e32 v[224:225], v[16:17]
	v_mov_b64_e32 v[192:193], v[10:11]
	v_mov_b64_e32 v[234:235], v[2:3]
	v_mov_b64_e32 v[194:195], v[12:13]
	v_mov_b64_e32 v[236:237], v[4:5]
	s_mov_b64 s[10:11], 0
